# grid barrier: non-leader blocks invalidate L1 on arrival instead of after release; XCD leader invalidates before publishing generation; NA attention permlane32 max
# speedup vs baseline: 1.0877x; 1.0267x over previous
.LBB0_46:
	s_cmp_eq_u32 s33, 0
	s_cselect_b64 vcc, -1, 0
	s_cmp_eq_u32 s33, 1
	v_cndmask_b32_e32 v18, 0, v17, vcc
	s_cselect_b64 vcc, -1, 0
	s_cmp_eq_u32 s33, 2
	v_cndmask_b32_e32 v18, v18, v4, vcc
	s_cselect_b64 vcc, -1, 0
	s_cmp_eq_u32 s33, 3
	v_cndmask_b32_e32 v18, v18, v8, vcc
	s_cselect_b64 vcc, -1, 0
	s_cmp_eq_u32 s33, 4
	v_cndmask_b32_e32 v18, v18, v9, vcc
	s_cselect_b64 vcc, -1, 0
	s_cmp_eq_u32 s33, 5
	v_cndmask_b32_e32 v18, v18, v10, vcc
	s_cselect_b64 vcc, -1, 0
	s_cmp_eq_u32 s33, 6
	v_cndmask_b32_e32 v18, v18, v11, vcc
	s_cselect_b64 vcc, -1, 0
	s_cmp_eq_u32 s33, 7
	v_cndmask_b32_e32 v18, v18, v12, vcc
	s_cselect_b64 vcc, -1, 0
	s_cmp_eq_u32 s33, 8
	v_cndmask_b32_e32 v18, v18, v13, vcc
	s_cselect_b64 vcc, -1, 0
	s_cmp_eq_u32 s33, 9
	v_cndmask_b32_e32 v18, v18, v14, vcc
	s_cselect_b64 vcc, -1, 0
	s_cmp_eq_u32 s33, 10
	v_cndmask_b32_e32 v18, v18, v15, vcc
	s_cselect_b64 vcc, -1, 0
	s_cmp_eq_u32 s33, 11
	v_cndmask_b32_e32 v18, v18, v16, vcc
	s_cselect_b64 vcc, -1, 0
	s_cmp_eq_u32 s33, 12
	v_cndmask_b32_e32 v18, v18, v6, vcc
	s_cselect_b64 vcc, -1, 0
	s_cmp_eq_u32 s33, 13
	v_cndmask_b32_e32 v18, v18, v7, vcc
	s_cselect_b64 vcc, -1, 0
	s_cmp_eq_u32 s33, 14
	v_cndmask_b32_e32 v18, v18, v3, vcc
	s_cselect_b64 vcc, -1, 0
	s_cmp_eq_u32 s33, 15
	v_cndmask_b32_e32 v18, v18, v5, vcc
	s_cselect_b64 vcc, -1, 0
	s_lshl_b32 s3, s33, 8
	s_add_u32 s8, s20, s3
	s_addc_u32 s9, s21, 0
	v_mov_b32_e32 v19, 0x1000
	v_mov_b32_e32 v20, 1
	global_atomic_add v19, v19, v20, s[8:9] offset:1024 sc0
	v_cndmask_b32_e32 v18, v18, v2, vcc
	v_cmp_ne_u32_e32 vcc, 0, v17
	s_nop 1
	v_cndmask_b32_e64 v17, 0, 1, vcc
	v_cmp_ne_u32_e32 vcc, 0, v4
	s_nop 1
	v_addc_co_u32_e32 v4, vcc, 0, v17, vcc
	v_cmp_ne_u32_e32 vcc, 0, v8
	s_nop 1
	v_cndmask_b32_e64 v8, 0, 1, vcc
	v_cmp_ne_u32_e32 vcc, 0, v9
	s_nop 1
	v_addc_co_u32_e32 v4, vcc, v4, v8, vcc
	v_cmp_ne_u32_e32 vcc, 0, v10
	s_nop 1
	v_cndmask_b32_e64 v8, 0, 1, vcc
	v_cmp_ne_u32_e32 vcc, 0, v11
	s_nop 1
	v_addc_co_u32_e32 v4, vcc, v4, v8, vcc
	v_cmp_ne_u32_e32 vcc, 0, v12
	s_nop 1
	v_cndmask_b32_e64 v8, 0, 1, vcc
	v_cmp_ne_u32_e32 vcc, 0, v13
	s_nop 1
	v_addc_co_u32_e32 v4, vcc, v4, v8, vcc
	v_cmp_ne_u32_e32 vcc, 0, v14
	s_nop 1
	v_cndmask_b32_e64 v8, 0, 1, vcc
	v_cmp_ne_u32_e32 vcc, 0, v15
	s_nop 1
	v_addc_co_u32_e32 v8, vcc, v4, v8, vcc
	v_max_u32_e32 v4, 1, v18
	v_cvt_f32_u32_e32 v10, v4
	v_cmp_ne_u32_e32 vcc, 0, v16
	s_nop 1
	v_cndmask_b32_e64 v9, 0, 1, vcc
	v_cmp_ne_u32_e32 vcc, 0, v6
	s_nop 1
	v_addc_co_u32_e32 v6, vcc, v8, v9, vcc
	v_rcp_iflag_f32_e32 v8, v10
	v_cmp_ne_u32_e32 vcc, 0, v7
	s_nop 1
	v_cndmask_b32_e64 v7, 0, 1, vcc
	v_cmp_ne_u32_e32 vcc, 0, v3
	s_nop 1
	v_addc_co_u32_e32 v3, vcc, v6, v7, vcc
	v_mul_f32_e32 v6, 0x4f7ffffe, v8
	v_cvt_u32_f32_e32 v6, v6
	v_cmp_ne_u32_e32 vcc, 0, v5
	s_nop 1
	v_cndmask_b32_e64 v5, 0, 1, vcc
	v_cmp_ne_u32_e32 vcc, 0, v2
	s_nop 1
	v_addc_co_u32_e32 v2, vcc, v3, v5, vcc
	v_sub_u32_e32 v3, 0, v4
	v_mul_lo_u32 v3, v3, v6
	v_mul_hi_u32 v3, v6, v3
	v_add_u32_e32 v3, v6, v3
	s_waitcnt vmcnt(0)
	v_mul_hi_u32 v3, v19, v3
	v_mul_lo_u32 v5, v3, v4
	v_sub_u32_e32 v5, v19, v5
	v_add_u32_e32 v6, 1, v3
	v_cmp_ge_u32_e32 vcc, v5, v4
	s_nop 1
	v_cndmask_b32_e32 v3, v3, v6, vcc
	v_sub_u32_e32 v6, v5, v4
	v_cndmask_b32_e32 v5, v5, v6, vcc
	v_add_u32_e32 v6, 1, v3
	v_cmp_ge_u32_e32 vcc, v5, v4
	v_add_u32_e32 v5, 1, v19
	s_nop 0
	v_cndmask_b32_e32 v3, v3, v6, vcc
	v_mul_lo_u32 v6, v4, v3
	v_add_u32_e32 v6, v6, v4
	v_cmp_ne_u32_e32 vcc, v5, v6
	s_and_saveexec_b64 s[10:11], vcc
	s_xor_b64 s[10:11], exec, s[10:11]
	s_cbranch_execz .LBB0_60
	v_mov_b32_e32 v5, 0x2000
	buffer_inv sc1
	global_load_dword v5, v5, s[8:9] offset:1024 sc1
	s_add_u32 s14, s8, 0x2400
	s_addc_u32 s15, s9, 0
	s_waitcnt vmcnt(0)
	v_cmp_eq_u32_e32 vcc, v5, v3
	s_and_saveexec_b64 s[12:13], vcc
	s_cbranch_execz .LBB0_59
	s_mov_b32 s3, 1
	s_mov_b64 s[16:17], 0
	v_mov_b32_e32 v5, 0
	s_branch .LBB0_50

.LBB0_59:
	s_or_b64 exec, exec, s[12:13]
	s_waitcnt vmcnt(0)
	s_waitcnt vmcnt(0)

.LBB0_77:
	s_or_b64 exec, exec, s[6:7]
	v_mov_b32_e32 v2, 0x2000
	v_mov_b32_e32 v3, 1
	s_waitcnt vmcnt(0)
	buffer_inv sc1
	s_waitcnt vmcnt(0)
	global_atomic_add v2, v3, s[8:9] offset:1024
	s_waitcnt vmcnt(0)

.LBB0_110:
	s_or_b64 exec, exec, s[6:7]
	s_lshl_b32 s3, s33, 8
	s_add_u32 s6, s20, s3
	s_addc_u32 s7, s21, 0
	v_mov_b32_e32 v3, 0x1000
	v_mov_b32_e32 v5, 1
	global_atomic_add v3, v3, v5, s[6:7] offset:1024 sc0
	v_cvt_f32_u32_e32 v5, v4
	v_sub_u32_e32 v6, 0, v4
	v_rcp_iflag_f32_e32 v5, v5
	s_nop 0
	v_mul_f32_e32 v5, 0x4f7ffffe, v5
	v_cvt_u32_f32_e32 v5, v5
	v_mul_lo_u32 v6, v6, v5
	v_mul_hi_u32 v6, v5, v6
	v_add_u32_e32 v5, v5, v6
	s_waitcnt vmcnt(0)
	v_mul_hi_u32 v5, v3, v5
	v_mul_lo_u32 v6, v5, v4
	v_add_u32_e32 v8, 1, v3
	v_sub_u32_e32 v3, v3, v6
	v_add_u32_e32 v7, 1, v5
	v_cmp_ge_u32_e32 vcc, v3, v4
	v_sub_u32_e32 v6, v3, v4
	s_nop 0
	v_cndmask_b32_e32 v5, v5, v7, vcc
	v_cndmask_b32_e32 v3, v3, v6, vcc
	v_add_u32_e32 v6, 1, v5
	v_cmp_ge_u32_e32 vcc, v3, v4
	s_nop 1
	v_cndmask_b32_e32 v3, v5, v6, vcc
	v_mad_u64_u32 v[6:7], s[8:9], v4, v3, v[4:5]
	v_cmp_ne_u32_e32 vcc, v8, v6
	s_and_saveexec_b64 s[8:9], vcc
	s_xor_b64 s[8:9], exec, s[8:9]
	s_cbranch_execz .LBB0_124
	v_mov_b32_e32 v5, 0x2000
	buffer_inv sc1
	global_load_dword v5, v5, s[6:7] offset:1024 sc1
	s_add_u32 s12, s6, 0x2400
	s_addc_u32 s13, s7, 0
	s_waitcnt vmcnt(0)
	v_cmp_eq_u32_e32 vcc, v5, v3
	s_and_saveexec_b64 s[10:11], vcc
	s_cbranch_execz .LBB0_123
	s_mov_b32 s3, 1
	s_mov_b64 s[14:15], 0
	v_mov_b32_e32 v5, 0
	s_branch .LBB0_114

.LBB0_123:
	s_or_b64 exec, exec, s[10:11]
	s_waitcnt vmcnt(0)
	s_waitcnt vmcnt(0)

.LBB0_141:
	s_or_b64 exec, exec, s[10:11]
	v_mov_b32_e32 v3, 0x2000
	v_mov_b32_e32 v5, 1
	s_waitcnt vmcnt(0)
	buffer_inv sc1
	s_waitcnt vmcnt(0)
	global_atomic_add v3, v5, s[6:7] offset:1024
	s_waitcnt vmcnt(0)

.LBB0_509:
	s_or_b64 exec, exec, s[6:7]
	s_lshl_b32 s3, s33, 8
	s_add_u32 s6, s20, s3
	s_addc_u32 s7, s21, 0
	v_mov_b32_e32 v5, 0x1000
	v_mov_b32_e32 v6, 1
	global_atomic_add v5, v5, v6, s[6:7] offset:1024 sc0
	v_cvt_f32_u32_e32 v6, v4
	v_sub_u32_e32 v7, 0, v4
	v_rcp_iflag_f32_e32 v6, v6
	s_nop 0
	v_mul_f32_e32 v6, 0x4f7ffffe, v6
	v_cvt_u32_f32_e32 v6, v6
	v_mul_lo_u32 v7, v7, v6
	v_mul_hi_u32 v7, v6, v7
	v_add_u32_e32 v6, v6, v7
	s_waitcnt vmcnt(0)
	v_mul_hi_u32 v6, v5, v6
	v_mul_lo_u32 v7, v6, v4
	v_add_u32_e32 v8, 1, v5
	v_sub_u32_e32 v5, v5, v7
	v_add_u32_e32 v9, 1, v6
	v_cmp_ge_u32_e32 vcc, v5, v4
	v_sub_u32_e32 v7, v5, v4
	s_nop 0
	v_cndmask_b32_e32 v6, v6, v9, vcc
	v_cndmask_b32_e32 v5, v5, v7, vcc
	v_add_u32_e32 v7, 1, v6
	v_cmp_ge_u32_e32 vcc, v5, v4
	s_nop 1
	v_cndmask_b32_e32 v5, v6, v7, vcc
	v_mad_u64_u32 v[6:7], s[8:9], v4, v5, v[4:5]
	v_cmp_ne_u32_e32 vcc, v8, v6
	s_and_saveexec_b64 s[8:9], vcc
	s_xor_b64 s[8:9], exec, s[8:9]
	s_cbranch_execz .LBB0_523
	v_mov_b32_e32 v6, 0x2000
	buffer_inv sc1
	global_load_dword v6, v6, s[6:7] offset:1024 sc1
	s_add_u32 s12, s6, 0x2400
	s_addc_u32 s13, s7, 0
	s_waitcnt vmcnt(0)
	v_cmp_eq_u32_e32 vcc, v6, v5
	s_and_saveexec_b64 s[10:11], vcc
	s_cbranch_execz .LBB0_522
	s_mov_b32 s3, 1
	s_mov_b64 s[14:15], 0
	v_mov_b32_e32 v6, 0
	s_branch .LBB0_513

.LBB0_540:
	s_or_b64 exec, exec, s[10:11]
	v_mov_b32_e32 v5, 0x2000
	v_mov_b32_e32 v6, 1
	s_waitcnt vmcnt(0)
	buffer_inv sc1
	s_waitcnt vmcnt(0)
	global_atomic_add v5, v6, s[6:7] offset:1024
	s_waitcnt vmcnt(0)

.LBB0_1226:
	s_or_b64 exec, exec, s[8:9]
	s_lshl_b32 s3, s33, 8
	s_add_u32 s6, s20, s3
	s_addc_u32 s7, s21, 0
	v_mov_b32_e32 v3, 0x1000
	v_mov_b32_e32 v5, 1
	global_atomic_add v3, v3, v5, s[6:7] offset:1024 sc0
	v_cvt_f32_u32_e32 v5, v4
	v_sub_u32_e32 v6, 0, v4
	v_rcp_iflag_f32_e32 v5, v5
	s_nop 0
	v_mul_f32_e32 v5, 0x4f7ffffe, v5
	v_cvt_u32_f32_e32 v5, v5
	v_mul_lo_u32 v6, v6, v5
	v_mul_hi_u32 v6, v5, v6
	v_add_u32_e32 v5, v5, v6
	s_waitcnt vmcnt(0)
	v_mul_hi_u32 v5, v3, v5
	v_mul_lo_u32 v6, v5, v4
	v_add_u32_e32 v8, 1, v3
	v_sub_u32_e32 v3, v3, v6
	v_add_u32_e32 v7, 1, v5
	v_cmp_ge_u32_e32 vcc, v3, v4
	v_sub_u32_e32 v6, v3, v4
	s_nop 0
	v_cndmask_b32_e32 v5, v5, v7, vcc
	v_cndmask_b32_e32 v3, v3, v6, vcc
	v_add_u32_e32 v6, 1, v5
	v_cmp_ge_u32_e32 vcc, v3, v4
	s_nop 1
	v_cndmask_b32_e32 v3, v5, v6, vcc
	v_mad_u64_u32 v[6:7], s[8:9], v4, v3, v[4:5]
	v_cmp_ne_u32_e32 vcc, v8, v6
	s_and_saveexec_b64 s[8:9], vcc
	s_xor_b64 s[8:9], exec, s[8:9]
	s_cbranch_execz .LBB0_1240
	v_mov_b32_e32 v5, 0x2000
	buffer_inv sc1
	global_load_dword v5, v5, s[6:7] offset:1024 sc1
	s_add_u32 s12, s6, 0x2400
	s_addc_u32 s13, s7, 0
	s_waitcnt vmcnt(0)
	v_cmp_eq_u32_e32 vcc, v5, v3
	s_and_saveexec_b64 s[10:11], vcc
	s_cbranch_execz .LBB0_1239
	s_mov_b32 s3, 1
	s_mov_b64 s[14:15], 0
	v_mov_b32_e32 v5, 0
	s_branch .LBB0_1230

.LBB0_1763:
	v_lshl_or_b32 v137, s9, 12, v106
	v_add_u32_e32 v34, v137, v107
	ds_read_b128 v[34:37], v34
	v_add_u32_e32 v38, v137, v109
	ds_read_b128 v[138:141], v38
	v_add_u32_e32 v142, v137, v111
	v_add_u32_e32 v137, v137, v113
	s_waitcnt lgkmcnt(0)
	v_mfma_f32_32x32x16_bf16 v[34:49], v[34:37], v[50:53], 0
	v_mfma_f32_32x32x16_bf16 v[34:49], v[138:141], v[54:57], v[34:49]
	ds_read_b128 v[138:141], v142
	ds_read_b128 v[142:145], v137
	s_waitcnt lgkmcnt(0)
	v_mfma_f32_32x32x16_bf16 v[34:49], v[138:141], v[58:61], v[34:49]
	v_mfma_f32_32x32x16_bf16 v[34:49], v[142:145], v[62:65], v[34:49]
	s_nop 11
	v_max_f32_e32 v137, v35, v35
	v_max_f32_e32 v138, v34, v34
	v_max_f32_e32 v137, v138, v137
	v_max3_f32 v137, v137, v36, v37
	v_max3_f32 v137, v137, v38, v39
	v_max3_f32 v137, v137, v40, v41
	v_max3_f32 v137, v137, v42, v43
	v_max3_f32 v137, v137, v44, v45
	v_max3_f32 v137, v137, v46, v47
	v_max3_f32 v137, v137, v48, v49
	v_mov_b32_e32 v138, v137
	s_nop 1
	v_permlane32_swap_b32_e32 v138, v137
	s_waitcnt lgkmcnt(0)
	v_max_f32_e32 v137, v137, v138
	v_add_f32_e32 v138, 0x41000000, v101
	v_cmp_gt_f32_e32 vcc, v137, v138
	s_cbranch_vccz .LBB0_1762
	v_max_f32_e32 v137, v137, v137
	v_max_f32_e32 v138, v101, v101
	v_max_f32_e32 v137, v138, v137
	v_sub_f32_e32 v101, v101, v137
	v_exp_f32_e32 v138, v101
	v_mov_b32_e32 v101, v137
	v_pk_mul_f32 v[16:17], v[16:17], v[138:139] op_sel_hi:[1,0]
	v_pk_mul_f32 v[14:15], v[14:15], v[138:139] op_sel_hi:[1,0]
	v_pk_mul_f32 v[12:13], v[12:13], v[138:139] op_sel_hi:[1,0]
	v_pk_mul_f32 v[10:11], v[10:11], v[138:139] op_sel_hi:[1,0]
	v_pk_mul_f32 v[8:9], v[8:9], v[138:139] op_sel_hi:[1,0]
	v_pk_mul_f32 v[6:7], v[6:7], v[138:139] op_sel_hi:[1,0]
	v_pk_mul_f32 v[4:5], v[4:5], v[138:139] op_sel_hi:[1,0]
	v_pk_mul_f32 v[2:3], v[2:3], v[138:139] op_sel_hi:[1,0]
	v_pk_mul_f32 v[32:33], v[32:33], v[138:139] op_sel_hi:[1,0]
	v_pk_mul_f32 v[30:31], v[30:31], v[138:139] op_sel_hi:[1,0]
	v_pk_mul_f32 v[28:29], v[28:29], v[138:139] op_sel_hi:[1,0]
	v_pk_mul_f32 v[26:27], v[26:27], v[138:139] op_sel_hi:[1,0]
	v_pk_mul_f32 v[24:25], v[24:25], v[138:139] op_sel_hi:[1,0]
	v_pk_mul_f32 v[22:23], v[22:23], v[138:139] op_sel_hi:[1,0]
	v_pk_mul_f32 v[20:21], v[20:21], v[138:139] op_sel_hi:[1,0]
	v_pk_mul_f32 v[18:19], v[18:19], v[138:139] op_sel_hi:[1,0]
	v_mul_f32_e32 v100, v100, v138
	s_branch .LBB0_1762

.LBB0_1767:
	v_lshl_or_b32 v137, s9, 12, v106
	v_add_u32_e32 v34, v137, v107
	ds_read_b128 v[34:37], v34 offset:16384
	v_add_u32_e32 v38, v137, v109
	ds_read_b128 v[138:141], v38 offset:16384
	v_add_u32_e32 v142, v137, v111
	v_add_u32_e32 v137, v137, v113
	s_waitcnt lgkmcnt(0)
	v_mfma_f32_32x32x16_bf16 v[34:49], v[34:37], v[50:53], 0
	v_mfma_f32_32x32x16_bf16 v[34:49], v[138:141], v[54:57], v[34:49]
	ds_read_b128 v[138:141], v142 offset:16384
	ds_read_b128 v[142:145], v137 offset:16384
	s_waitcnt lgkmcnt(0)
	v_mfma_f32_32x32x16_bf16 v[34:49], v[138:141], v[58:61], v[34:49]
	v_mfma_f32_32x32x16_bf16 v[34:49], v[142:145], v[62:65], v[34:49]
	s_nop 11
	v_max_f32_e32 v137, v35, v35
	v_max_f32_e32 v138, v34, v34
	v_max_f32_e32 v137, v138, v137
	v_max3_f32 v137, v137, v36, v37
	v_max3_f32 v137, v137, v38, v39
	v_max3_f32 v137, v137, v40, v41
	v_max3_f32 v137, v137, v42, v43
	v_max3_f32 v137, v137, v44, v45
	v_max3_f32 v137, v137, v46, v47
	v_max3_f32 v137, v137, v48, v49
	v_mov_b32_e32 v138, v137
	s_nop 1
	v_permlane32_swap_b32_e32 v138, v137
	s_waitcnt lgkmcnt(0)
	v_max_f32_e32 v137, v137, v138
	v_add_f32_e32 v138, 0x41000000, v101
	v_cmp_gt_f32_e32 vcc, v137, v138
	s_cbranch_vccz .LBB0_1766
	v_max_f32_e32 v137, v137, v137
	v_max_f32_e32 v138, v101, v101
	v_max_f32_e32 v137, v138, v137
	v_sub_f32_e32 v101, v101, v137
	v_exp_f32_e32 v138, v101
	v_mov_b32_e32 v101, v137
	v_pk_mul_f32 v[16:17], v[16:17], v[138:139] op_sel_hi:[1,0]
	v_pk_mul_f32 v[14:15], v[14:15], v[138:139] op_sel_hi:[1,0]
	v_pk_mul_f32 v[12:13], v[12:13], v[138:139] op_sel_hi:[1,0]
	v_pk_mul_f32 v[10:11], v[10:11], v[138:139] op_sel_hi:[1,0]
	v_pk_mul_f32 v[8:9], v[8:9], v[138:139] op_sel_hi:[1,0]
	v_pk_mul_f32 v[6:7], v[6:7], v[138:139] op_sel_hi:[1,0]
	v_pk_mul_f32 v[4:5], v[4:5], v[138:139] op_sel_hi:[1,0]
	v_pk_mul_f32 v[2:3], v[2:3], v[138:139] op_sel_hi:[1,0]
	v_pk_mul_f32 v[32:33], v[32:33], v[138:139] op_sel_hi:[1,0]
	v_pk_mul_f32 v[30:31], v[30:31], v[138:139] op_sel_hi:[1,0]
	v_pk_mul_f32 v[28:29], v[28:29], v[138:139] op_sel_hi:[1,0]
	v_pk_mul_f32 v[26:27], v[26:27], v[138:139] op_sel_hi:[1,0]
	v_pk_mul_f32 v[24:25], v[24:25], v[138:139] op_sel_hi:[1,0]
	v_pk_mul_f32 v[22:23], v[22:23], v[138:139] op_sel_hi:[1,0]
	v_pk_mul_f32 v[20:21], v[20:21], v[138:139] op_sel_hi:[1,0]
	v_pk_mul_f32 v[18:19], v[18:19], v[138:139] op_sel_hi:[1,0]
	v_mul_f32_e32 v100, v100, v138
	s_branch .LBB0_1766

.LBB0_1771:
	v_lshl_or_b32 v137, s9, 12, v106
	v_add_u32_e32 v34, v137, v107
	ds_read_b128 v[34:37], v34
	v_add_u32_e32 v38, v137, v109
	ds_read_b128 v[96:99], v38
	v_add_u32_e32 v138, v137, v111
	v_add_u32_e32 v137, v137, v113
	s_waitcnt lgkmcnt(0)
	v_mfma_f32_32x32x16_bf16 v[34:49], v[34:37], v[50:53], 0
	v_mfma_f32_32x32x16_bf16 v[34:49], v[96:99], v[54:57], v[34:49]
	ds_read_b128 v[96:99], v138
	ds_read_b128 v[138:141], v137
	s_waitcnt lgkmcnt(0)
	v_mfma_f32_32x32x16_bf16 v[34:49], v[96:99], v[58:61], v[34:49]
	v_mfma_f32_32x32x16_bf16 v[34:49], v[138:141], v[62:65], v[34:49]
	s_nop 11
	v_max_f32_e32 v96, v35, v35
	v_max_f32_e32 v97, v34, v34
	v_max_f32_e32 v96, v97, v96
	v_max3_f32 v96, v96, v36, v37
	v_max3_f32 v96, v96, v38, v39
	v_max3_f32 v96, v96, v40, v41
	v_max3_f32 v96, v96, v42, v43
	v_max3_f32 v96, v96, v44, v45
	v_max3_f32 v96, v96, v46, v47
	v_max3_f32 v96, v96, v48, v49
	v_mov_b32_e32 v97, v96
	s_nop 1
	v_permlane32_swap_b32_e32 v97, v96
	s_waitcnt lgkmcnt(0)
	v_max_f32_e32 v96, v96, v97
	v_add_f32_e32 v97, 0x41000000, v101
	v_cmp_gt_f32_e32 vcc, v96, v97
	s_cbranch_vccz .LBB0_1770
	v_max_f32_e32 v96, v96, v96
	v_max_f32_e32 v97, v101, v101
	v_max_f32_e32 v97, v97, v96
	v_sub_f32_e32 v96, v101, v97
	v_exp_f32_e32 v96, v96
	v_mov_b32_e32 v101, v97
	v_pk_mul_f32 v[16:17], v[16:17], v[96:97] op_sel_hi:[1,0]
	v_pk_mul_f32 v[14:15], v[14:15], v[96:97] op_sel_hi:[1,0]
	v_pk_mul_f32 v[12:13], v[12:13], v[96:97] op_sel_hi:[1,0]
	v_pk_mul_f32 v[10:11], v[10:11], v[96:97] op_sel_hi:[1,0]
	v_pk_mul_f32 v[8:9], v[8:9], v[96:97] op_sel_hi:[1,0]
	v_pk_mul_f32 v[6:7], v[6:7], v[96:97] op_sel_hi:[1,0]
	v_pk_mul_f32 v[4:5], v[4:5], v[96:97] op_sel_hi:[1,0]
	v_pk_mul_f32 v[2:3], v[2:3], v[96:97] op_sel_hi:[1,0]
	v_pk_mul_f32 v[32:33], v[32:33], v[96:97] op_sel_hi:[1,0]
	v_pk_mul_f32 v[30:31], v[30:31], v[96:97] op_sel_hi:[1,0]
	v_pk_mul_f32 v[28:29], v[28:29], v[96:97] op_sel_hi:[1,0]
	v_pk_mul_f32 v[26:27], v[26:27], v[96:97] op_sel_hi:[1,0]
	v_pk_mul_f32 v[24:25], v[24:25], v[96:97] op_sel_hi:[1,0]
	v_pk_mul_f32 v[22:23], v[22:23], v[96:97] op_sel_hi:[1,0]
	v_pk_mul_f32 v[20:21], v[20:21], v[96:97] op_sel_hi:[1,0]
	v_pk_mul_f32 v[18:19], v[18:19], v[96:97] op_sel_hi:[1,0]
	v_mul_f32_e32 v100, v100, v96
	s_branch .LBB0_1770

.LBB0_1775:
	v_lshl_or_b32 v137, s9, 12, v106
	v_add_u32_e32 v34, v137, v107
	ds_read_b128 v[34:37], v34 offset:16384
	v_add_u32_e32 v38, v137, v109
	ds_read_b128 v[96:99], v38 offset:16384
	v_add_u32_e32 v138, v137, v111
	v_add_u32_e32 v137, v137, v113
	s_waitcnt lgkmcnt(1)
	v_mfma_f32_32x32x16_bf16 v[34:49], v[34:37], v[50:53], 0
	s_waitcnt lgkmcnt(0)
	v_mfma_f32_32x32x16_bf16 v[34:49], v[96:99], v[54:57], v[34:49]
	ds_read_b128 v[96:99], v138 offset:16384
	ds_read_b128 v[138:141], v137 offset:16384
	s_waitcnt lgkmcnt(1)
	v_mfma_f32_32x32x16_bf16 v[34:49], v[96:99], v[58:61], v[34:49]
	s_waitcnt lgkmcnt(0)
	v_mfma_f32_32x32x16_bf16 v[34:49], v[138:141], v[62:65], v[34:49]
	s_nop 11
	v_max_f32_e32 v96, v35, v35
	v_max_f32_e32 v97, v34, v34
	v_max_f32_e32 v96, v97, v96
	v_max3_f32 v96, v96, v36, v37
	v_max3_f32 v96, v96, v38, v39
	v_max3_f32 v96, v96, v40, v41
	v_max3_f32 v96, v96, v42, v43
	v_max3_f32 v96, v96, v44, v45
	v_max3_f32 v96, v96, v46, v47
	v_max3_f32 v96, v96, v48, v49
	v_mov_b32_e32 v97, v96
	s_nop 1
	v_permlane32_swap_b32_e32 v97, v96
	s_waitcnt lgkmcnt(0)
	v_max_f32_e32 v96, v96, v97
	v_add_f32_e32 v97, 0x41000000, v101
	v_cmp_gt_f32_e32 vcc, v96, v97
	s_cbranch_vccz .LBB0_1774
	v_max_f32_e32 v96, v96, v96
	v_max_f32_e32 v97, v101, v101
	v_max_f32_e32 v97, v97, v96
	v_sub_f32_e32 v96, v101, v97
	v_exp_f32_e32 v96, v96
	v_mov_b32_e32 v101, v97
	v_pk_mul_f32 v[16:17], v[16:17], v[96:97] op_sel_hi:[1,0]
	v_pk_mul_f32 v[14:15], v[14:15], v[96:97] op_sel_hi:[1,0]
	v_pk_mul_f32 v[12:13], v[12:13], v[96:97] op_sel_hi:[1,0]
	v_pk_mul_f32 v[10:11], v[10:11], v[96:97] op_sel_hi:[1,0]
	v_pk_mul_f32 v[8:9], v[8:9], v[96:97] op_sel_hi:[1,0]
	v_pk_mul_f32 v[6:7], v[6:7], v[96:97] op_sel_hi:[1,0]
	v_pk_mul_f32 v[4:5], v[4:5], v[96:97] op_sel_hi:[1,0]
	v_pk_mul_f32 v[2:3], v[2:3], v[96:97] op_sel_hi:[1,0]
	v_pk_mul_f32 v[32:33], v[32:33], v[96:97] op_sel_hi:[1,0]
	v_pk_mul_f32 v[30:31], v[30:31], v[96:97] op_sel_hi:[1,0]
	v_pk_mul_f32 v[28:29], v[28:29], v[96:97] op_sel_hi:[1,0]
	v_pk_mul_f32 v[26:27], v[26:27], v[96:97] op_sel_hi:[1,0]
	v_pk_mul_f32 v[24:25], v[24:25], v[96:97] op_sel_hi:[1,0]
	v_pk_mul_f32 v[22:23], v[22:23], v[96:97] op_sel_hi:[1,0]
	v_pk_mul_f32 v[20:21], v[20:21], v[96:97] op_sel_hi:[1,0]
	v_pk_mul_f32 v[18:19], v[18:19], v[96:97] op_sel_hi:[1,0]
	v_mul_f32_e32 v100, v100, v96
	s_branch .LBB0_1774

.LBB0_1794:
	s_nop 10
	v_max_f32_e32 v145, v35, v35
	v_max_f32_e32 v147, v34, v34
	v_max_f32_e32 v145, v147, v145
	v_max3_f32 v145, v145, v36, v37
	v_max3_f32 v145, v145, v38, v39
	v_max3_f32 v145, v145, v40, v41
	v_max3_f32 v145, v145, v42, v43
	v_max3_f32 v145, v145, v44, v45
	v_max3_f32 v145, v145, v46, v47
	v_max3_f32 v145, v145, v48, v49
	v_mov_b32_e32 v147, v145
	s_nop 1
	v_permlane32_swap_b32_e32 v147, v145
	s_waitcnt lgkmcnt(0)
	v_max_f32_e32 v145, v145, v147
	v_add_f32_e32 v147, 0x41000000, v141
	v_cmp_gt_f32_e32 vcc, v145, v147
	s_cbranch_vccz .LBB0_1791
	v_max_f32_e32 v145, v145, v145
	v_max_f32_e32 v147, v141, v141
	v_max_f32_e32 v145, v147, v145
	v_sub_f32_e32 v141, v141, v145
	v_exp_f32_e32 v152, v141
	v_mov_b32_e32 v141, v145
	v_pk_mul_f32 v[16:17], v[16:17], v[152:153] op_sel_hi:[1,0]
	v_pk_mul_f32 v[14:15], v[14:15], v[152:153] op_sel_hi:[1,0]
	v_pk_mul_f32 v[12:13], v[12:13], v[152:153] op_sel_hi:[1,0]
	v_pk_mul_f32 v[10:11], v[10:11], v[152:153] op_sel_hi:[1,0]
	v_pk_mul_f32 v[8:9], v[8:9], v[152:153] op_sel_hi:[1,0]
	v_pk_mul_f32 v[6:7], v[6:7], v[152:153] op_sel_hi:[1,0]
	v_pk_mul_f32 v[4:5], v[4:5], v[152:153] op_sel_hi:[1,0]
	v_pk_mul_f32 v[2:3], v[2:3], v[152:153] op_sel_hi:[1,0]
	v_pk_mul_f32 v[32:33], v[32:33], v[152:153] op_sel_hi:[1,0]
	v_pk_mul_f32 v[30:31], v[30:31], v[152:153] op_sel_hi:[1,0]
	v_pk_mul_f32 v[28:29], v[28:29], v[152:153] op_sel_hi:[1,0]
	v_pk_mul_f32 v[26:27], v[26:27], v[152:153] op_sel_hi:[1,0]
	v_pk_mul_f32 v[24:25], v[24:25], v[152:153] op_sel_hi:[1,0]
	v_pk_mul_f32 v[22:23], v[22:23], v[152:153] op_sel_hi:[1,0]
	v_pk_mul_f32 v[20:21], v[20:21], v[152:153] op_sel_hi:[1,0]
	v_pk_mul_f32 v[18:19], v[18:19], v[152:153] op_sel_hi:[1,0]
	v_mul_f32_e32 v93, v93, v152
	s_branch .LBB0_1791

.LBB0_2351:
	s_or_b64 exec, exec, s[4:5]
	s_lshl_b32 s4, s33, 8
	s_add_u32 s4, s20, s4
	s_addc_u32 s5, s21, 0
	v_mov_b32_e32 v3, 0x1000
	v_mov_b32_e32 v5, 1
	global_atomic_add v3, v3, v5, s[4:5] offset:1024 sc0
	v_cvt_f32_u32_e32 v5, v4
	v_sub_u32_e32 v6, 0, v4
	v_rcp_iflag_f32_e32 v5, v5
	s_nop 0
	v_mul_f32_e32 v5, 0x4f7ffffe, v5
	v_cvt_u32_f32_e32 v5, v5
	v_mul_lo_u32 v6, v6, v5
	v_mul_hi_u32 v6, v5, v6
	v_add_u32_e32 v5, v5, v6
	s_waitcnt vmcnt(0)
	v_mul_hi_u32 v5, v3, v5
	v_mul_lo_u32 v6, v5, v4
	v_add_u32_e32 v8, 1, v3
	v_sub_u32_e32 v3, v3, v6
	v_add_u32_e32 v7, 1, v5
	v_cmp_ge_u32_e32 vcc, v3, v4
	v_sub_u32_e32 v6, v3, v4
	s_nop 0
	v_cndmask_b32_e32 v5, v5, v7, vcc
	v_cndmask_b32_e32 v3, v3, v6, vcc
	v_add_u32_e32 v6, 1, v5
	v_cmp_ge_u32_e32 vcc, v3, v4
	s_nop 1
	v_cndmask_b32_e32 v3, v5, v6, vcc
	v_mad_u64_u32 v[6:7], s[6:7], v4, v3, v[4:5]
	v_cmp_ne_u32_e32 vcc, v8, v6
	s_and_saveexec_b64 s[6:7], vcc
	s_xor_b64 s[6:7], exec, s[6:7]
	s_cbranch_execz .LBB0_2365
	v_mov_b32_e32 v5, 0x2000
	buffer_inv sc1
	global_load_dword v5, v5, s[4:5] offset:1024 sc1
	s_add_u32 s10, s4, 0x2400
	s_addc_u32 s11, s5, 0
	s_waitcnt vmcnt(0)
	v_cmp_eq_u32_e32 vcc, v5, v3
	s_and_saveexec_b64 s[8:9], vcc
	s_cbranch_execz .LBB0_2364
	s_mov_b32 s26, 1
	s_mov_b64 s[12:13], 0
	v_mov_b32_e32 v5, 0
	s_branch .LBB0_2355

.LBB0_2364:
	s_or_b64 exec, exec, s[8:9]
	s_waitcnt vmcnt(0)
	s_waitcnt vmcnt(0)

.LBB0_2382:
	s_or_b64 exec, exec, s[8:9]
	v_mov_b32_e32 v3, 0x2000
	v_mov_b32_e32 v5, 1
	s_waitcnt vmcnt(0)
	buffer_inv sc1
	s_waitcnt vmcnt(0)
	global_atomic_add v3, v5, s[4:5] offset:1024
	s_waitcnt vmcnt(0)

.LBB0_2416:
	s_or_b64 exec, exec, s[4:5]
	s_lshl_b32 s4, s33, 8
	s_add_u32 s4, s20, s4
	s_addc_u32 s5, s21, 0
	v_mov_b32_e32 v1, 0x1000
	v_mov_b32_e32 v2, 1
	global_atomic_add v1, v1, v2, s[4:5] offset:1024 sc0
	v_cvt_f32_u32_e32 v2, v148
	v_sub_u32_e32 v3, 0, v148
	v_rcp_iflag_f32_e32 v2, v2
	s_nop 0
	v_mul_f32_e32 v2, 0x4f7ffffe, v2
	v_cvt_u32_f32_e32 v2, v2
	v_mul_lo_u32 v3, v3, v2
	v_mul_hi_u32 v3, v2, v3
	v_add_u32_e32 v2, v2, v3
	s_waitcnt vmcnt(0)
	v_mul_hi_u32 v2, v1, v2
	v_mul_lo_u32 v3, v2, v148
	v_add_u32_e32 v4, 1, v1
	v_sub_u32_e32 v1, v1, v3
	v_add_u32_e32 v5, 1, v2
	v_cmp_ge_u32_e32 vcc, v1, v148
	v_sub_u32_e32 v3, v1, v148
	s_nop 0
	v_cndmask_b32_e32 v2, v2, v5, vcc
	v_cndmask_b32_e32 v1, v1, v3, vcc
	v_add_u32_e32 v3, 1, v2
	v_cmp_ge_u32_e32 vcc, v1, v148
	s_nop 1
	v_cndmask_b32_e32 v1, v2, v3, vcc
	v_mad_u64_u32 v[2:3], s[8:9], v148, v1, v[148:149]
	v_cmp_ne_u32_e32 vcc, v4, v2
	s_and_saveexec_b64 s[8:9], vcc
	s_xor_b64 s[8:9], exec, s[8:9]
	s_cbranch_execz .LBB0_2430
	v_mov_b32_e32 v2, 0x2000
	buffer_inv sc1
	global_load_dword v2, v2, s[4:5] offset:1024 sc1
	s_add_u32 s12, s4, 0x2400
	s_addc_u32 s13, s5, 0
	s_waitcnt vmcnt(0)
	v_cmp_eq_u32_e32 vcc, v2, v1
	s_and_saveexec_b64 s[10:11], vcc
	s_cbranch_execz .LBB0_2429
	s_mov_b32 s26, 1
	s_mov_b64 s[14:15], 0
	v_mov_b32_e32 v2, 0
	s_branch .LBB0_2420

.LBB0_2447:
	s_or_b64 exec, exec, s[8:9]
	v_mov_b32_e32 v1, 0x2000
	v_mov_b32_e32 v2, 1
	s_waitcnt vmcnt(0)
	buffer_inv sc1
	s_waitcnt vmcnt(0)
	global_atomic_add v1, v2, s[4:5] offset:1024
	s_waitcnt vmcnt(0)
